# sample attention item loop hand-rewritten: K/V cache rows streamed through an 8-deep register ring (32 loads in flight) instead of one HBM round trip per 4 keys; same f32 math
# speedup vs baseline: 1.0038x; 1.0038x over previous
; __device__ __forceinline__ float fexp2(float x) { return __builtin_amdgcn_exp2f(x); }
; __device__ __forceinline__ void attn_sample_item(const P& p, int wi, int lane) {
;     ...
;     const int srow = bs * 4 + i;
;     const float* ACC1 = (const float*)(ws + O_ACC1); const float* rstd1 = (const float*)(ws + O_RSTD1);
;     float q[8];
;     { const float rq = rstd1[TP + srow] * (0.08838834764831845f * LOG2E);
;       const f32x4 q0 = acc1_4(ACC1, srow, 3072 + h * 128 + 8 * li), q1 = acc1_4(ACC1, srow, 3072 + h * 128 + 8 * li + 4);
;       q[0] = q0[0] * rq; q[1] = q0[1] * rq; q[2] = q0[2] * rq; q[3] = q0[3] * rq; q[4] = q1[0] * rq; q[5] = q1[1] * rq; q[6] = q1[2] * rq; q[7] = q1[3] * rq; }
;     if (kg == 0) {
;         const float rs = rstd1[TP + srow];
;         float* ko = p.out + OUT_KN + (size_t)srow * 1024 + h * 128 + 8 * li; float* vo = p.out + OUT_VN + (size_t)srow * 1024 + h * 128 + 8 * li;
;         *(f32x4*)ko = acc1_4(ACC1, srow, 4096 + h * 128 + 8 * li) * rs; *(f32x4*)(ko + 4) = acc1_4(ACC1, srow, 4096 + h * 128 + 8 * li + 4) * rs;
;         *(f32x4*)vo = acc1_4(ACC1, srow, 5120 + h * 128 + 8 * li) * rs; *(f32x4*)(vo + 4) = acc1_4(ACC1, srow, 5120 + h * 128 + 8 * li + 4) * rs;
;     }
;     float m = -1e30f, l = 0.f, acc[8];
; #pragma unroll
;     for (int e = 0; e < 8; ++e) acc[e] = 0.f;
;     const float sl = fexp2(-(float)(h + 1)) * LOG2E;
;     for (int g = 0; g < 3; ++g) {
;         const int d = 1 << (2 * g);
; #pragma unroll 3
;         for (int jj = 0; jj < 33; ++jj) {
;             const int j = 4 * jj + kg; const bool valid = j <= 128; const int jc = valid ? j : 128;
;             const int idx = 2048 + i - d * jc;
;             f32x4 k0, k1, v0, v1;
;             if (idx < 2048) { const size_t off = (((size_t)bs * 2048 + idx) * 8 + h) * 128 + 8 * li;
;                 k0 = __builtin_nontemporal_load((const f32x4*)(p.cache_k + off)); k1 = __builtin_nontemporal_load((const f32x4*)(p.cache_k + off + 4)); v0 = __builtin_nontemporal_load((const f32x4*)(p.cache_v + off)); v1 = __builtin_nontemporal_load((const f32x4*)(p.cache_v + off + 4)); }
;             else { const int nr = bs * 4 + (idx - 2048); const float rsn = rstd1[TP + nr]; const int c0 = 4096 + h * 128 + 8 * li;
;                 k0 = acc1_4(ACC1, nr, c0) * rsn; k1 = acc1_4(ACC1, nr, c0 + 4) * rsn; v0 = acc1_4(ACC1, nr, c0 + 1024) * rsn; v1 = acc1_4(ACC1, nr, c0 + 1028) * rsn; }
.LBB0_453:
	s_andn2_b64 vcc, exec, s[0:1]
	s_cbranch_vccnz .LBB0_479
	s_mul_i32 s0, s3, s34
	s_add_i32 s3, s0, s2
	s_cmpk_gt_i32 s3, 0x3ff
	s_cbranch_scc1 .LBB0_479
	s_lshl_b32 s77, s34, 2
	s_add_u32 s26, s68, 0x6200000
	s_addc_u32 s27, s69, 0
	s_add_u32 s28, s68, 0x6280000
	s_addc_u32 s29, s69, 0
	s_add_u32 s30, s70, 0x183a6400
	s_addc_u32 s31, s71, 0
.Las_item:
	s_ashr_i32 s14, s3, 5
	s_bfe_u32 s15, s3, 0x20003
	s_and_b32 s16, s3, 7
	s_lshl_b32 s17, s14, 2
	s_or_b32 s17, s17, s15
	s_lshl_b32 s18, s14, 23
	s_add_u32 s20, s56, s18
	s_addc_u32 s21, s57, 0
	s_add_u32 s24, s58, s18
	s_addc_u32 s25, s59, 0
	s_lshl_b32 s18, s17, 2
	s_add_u32 s18, s18, 0x8000
	s_load_dword s19, s[10:11], s18
	s_lshl_b32 s23, s16, 9
	v_and_b32_e32 v72, 15, v230
	v_lshlrev_b32_e32 v72, 5, v72
	v_bfe_u32 v73, v230, 4, 2
	v_cvt_f32_u32_e32 v202, v73
	v_add_u32_e32 v72, s23, v72
	s_add_u32 s43, s15, 0x800
	s_lshl_b32 s43, s43, 12
	v_add_u32_e32 v203, s43, v72
	s_sub_u32 s43, 0x7a, s16
	s_lshl_b32 s43, s43, 23
	v_mov_b32_e32 v201, s43
	v_mul_f32_e32 v201, 0xbfb8aa3b, v201
	s_mul_i32 s43, s17, 0x6000
	s_add_u32 s43, s43, 0x3000
	v_add_u32_e32 v64, s43, v72
	v_sub_u32_e32 v67, s15, v73
	v_max_i32_e32 v67, 0, v67
	v_lshl_add_u32 v67, s14, 2, v67
	v_lshlrev_b32_e32 v66, 2, v67
	v_add_u32_e32 v66, 0x8000, v66
	v_mul_u32_u24_e32 v65, 0x6000, v67
	v_add_u32_e32 v65, 0x4000, v65
	v_add_u32_e32 v65, v65, v72
	v_lshlrev_b32_e32 v68, 12, v73
	v_sub_u32_e32 v68, v203, v68
	s_mov_b32 s43, 0x7ff000
	v_add_u32_e32 v69, s43, v72
	v_min_u32_e32 v68, v68, v69
	v_add_u32_e32 v69, 0xfff80000, v203
	global_load_dword v70, v66, s[10:11]
	global_load_dwordx4 v[128:131], v68, s[20:21]
	global_load_dwordx4 v[132:135], v68, s[20:21] offset:16
	global_load_dwordx4 v[136:139], v68, s[24:25]
	global_load_dwordx4 v[140:143], v68, s[24:25] offset:16
	global_load_dwordx4 v[144:147], v69, s[20:21]
	global_load_dwordx4 v[148:151], v69, s[20:21] offset:16
	global_load_dwordx4 v[152:155], v69, s[24:25]
	global_load_dwordx4 v[156:159], v69, s[24:25] offset:16
	v_mov_b32_e32 v71, v64
	global_load_dwordx4 v[0:3], v71, s[8:9]
	v_add_u32_e32 v71, 0x300000, v71
	global_load_dwordx4 v[4:7], v71, s[8:9]
	v_add_u32_e32 v71, 0x300000, v71
	global_load_dwordx4 v[8:11], v71, s[8:9]
	v_add_u32_e32 v71, 0x300000, v71
	global_load_dwordx4 v[12:15], v71, s[8:9]
	v_add_u32_e32 v71, 0x300000, v71
	global_load_dwordx4 v[16:19], v71, s[8:9]
	v_add_u32_e32 v71, 0x300000, v71
	global_load_dwordx4 v[20:23], v71, s[8:9]
	v_add_u32_e32 v71, 0x300000, v71
	global_load_dwordx4 v[24:27], v71, s[8:9]
	v_add_u32_e32 v71, 0x300000, v71
	global_load_dwordx4 v[28:31], v71, s[8:9]
	v_mov_b32_e32 v71, v64
	global_load_dwordx4 v[32:35], v71, s[8:9] offset:16
	v_add_u32_e32 v71, 0x300000, v71
	global_load_dwordx4 v[36:39], v71, s[8:9] offset:16
	v_add_u32_e32 v71, 0x300000, v71
	global_load_dwordx4 v[40:43], v71, s[8:9] offset:16
	v_add_u32_e32 v71, 0x300000, v71
	global_load_dwordx4 v[44:47], v71, s[8:9] offset:16
	v_add_u32_e32 v71, 0x300000, v71
	global_load_dwordx4 v[48:51], v71, s[8:9] offset:16
	v_add_u32_e32 v71, 0x300000, v71
	global_load_dwordx4 v[52:55], v71, s[8:9] offset:16
	v_add_u32_e32 v71, 0x300000, v71
	global_load_dwordx4 v[56:59], v71, s[8:9] offset:16
	v_add_u32_e32 v71, 0x300000, v71
	global_load_dwordx4 v[60:63], v71, s[8:9] offset:16
	s_waitcnt vmcnt(8)
	v_add_f32_e32 v160, v0, v4
	v_add_f32_e32 v161, v1, v5
	v_add_f32_e32 v162, v2, v6
	v_add_f32_e32 v163, v3, v7
	v_add_f32_e32 v160, v160, v8
	v_add_f32_e32 v161, v161, v9
	v_add_f32_e32 v162, v162, v10
	v_add_f32_e32 v163, v163, v11
	v_add_f32_e32 v160, v160, v12
	v_add_f32_e32 v161, v161, v13
	v_add_f32_e32 v162, v162, v14
	v_add_f32_e32 v163, v163, v15
	v_add_f32_e32 v160, v160, v16
	v_add_f32_e32 v161, v161, v17
	v_add_f32_e32 v162, v162, v18
	v_add_f32_e32 v163, v163, v19
	v_add_f32_e32 v160, v160, v20
	v_add_f32_e32 v161, v161, v21
	v_add_f32_e32 v162, v162, v22
	v_add_f32_e32 v163, v163, v23
	v_add_f32_e32 v160, v160, v24
	v_add_f32_e32 v161, v161, v25
	v_add_f32_e32 v162, v162, v26
	v_add_f32_e32 v163, v163, v27
	v_add_f32_e32 v160, v160, v28
	v_add_f32_e32 v161, v161, v29
	v_add_f32_e32 v162, v162, v30
	v_add_f32_e32 v163, v163, v31
	v_mov_b32_e32 v71, v65
	global_load_dwordx4 v[0:3], v71, s[8:9]
	v_add_u32_e32 v71, 0x300000, v71
	global_load_dwordx4 v[4:7], v71, s[8:9]
	v_add_u32_e32 v71, 0x300000, v71
	global_load_dwordx4 v[8:11], v71, s[8:9]
	v_add_u32_e32 v71, 0x300000, v71
	global_load_dwordx4 v[12:15], v71, s[8:9]
	v_add_u32_e32 v71, 0x300000, v71
	global_load_dwordx4 v[16:19], v71, s[8:9]
	v_add_u32_e32 v71, 0x300000, v71
	global_load_dwordx4 v[20:23], v71, s[8:9]
	v_add_u32_e32 v71, 0x300000, v71
	global_load_dwordx4 v[24:27], v71, s[8:9]
	v_add_u32_e32 v71, 0x300000, v71
	global_load_dwordx4 v[28:31], v71, s[8:9]
	s_waitcnt vmcnt(8)
	v_add_f32_e32 v164, v32, v36
	v_add_f32_e32 v165, v33, v37
	v_add_f32_e32 v166, v34, v38
	v_add_f32_e32 v167, v35, v39
	v_add_f32_e32 v164, v164, v40
	v_add_f32_e32 v165, v165, v41
	v_add_f32_e32 v166, v166, v42
	v_add_f32_e32 v167, v167, v43
	v_add_f32_e32 v164, v164, v44
	v_add_f32_e32 v165, v165, v45
	v_add_f32_e32 v166, v166, v46
	v_add_f32_e32 v167, v167, v47
	v_add_f32_e32 v164, v164, v48
	v_add_f32_e32 v165, v165, v49
	v_add_f32_e32 v166, v166, v50
	v_add_f32_e32 v167, v167, v51
	v_add_f32_e32 v164, v164, v52
	v_add_f32_e32 v165, v165, v53
	v_add_f32_e32 v166, v166, v54
	v_add_f32_e32 v167, v167, v55
	v_add_f32_e32 v164, v164, v56
	v_add_f32_e32 v165, v165, v57
	v_add_f32_e32 v166, v166, v58
	v_add_f32_e32 v167, v167, v59
	v_add_f32_e32 v164, v164, v60
	v_add_f32_e32 v165, v165, v61
	v_add_f32_e32 v166, v166, v62
	v_add_f32_e32 v167, v167, v63
	v_mov_b32_e32 v71, v65
	global_load_dwordx4 v[32:35], v71, s[8:9] offset:16
	v_add_u32_e32 v71, 0x300000, v71
	global_load_dwordx4 v[36:39], v71, s[8:9] offset:16
	v_add_u32_e32 v71, 0x300000, v71
	global_load_dwordx4 v[40:43], v71, s[8:9] offset:16
	v_add_u32_e32 v71, 0x300000, v71
	global_load_dwordx4 v[44:47], v71, s[8:9] offset:16
	v_add_u32_e32 v71, 0x300000, v71
	global_load_dwordx4 v[48:51], v71, s[8:9] offset:16
	v_add_u32_e32 v71, 0x300000, v71
	global_load_dwordx4 v[52:55], v71, s[8:9] offset:16
	v_add_u32_e32 v71, 0x300000, v71
	global_load_dwordx4 v[56:59], v71, s[8:9] offset:16
	v_add_u32_e32 v71, 0x300000, v71
	global_load_dwordx4 v[60:63], v71, s[8:9] offset:16
	s_waitcnt vmcnt(8)
; __device__ __forceinline__ f32x4 acc1_4(const float* ACC1, int srow, int col) {
;     f32x4 s = *(const f32x4*)(ACC1 + (size_t)srow * N1 + col);
; #pragma unroll
;     for (int kp = 1; kp < 8; ++kp) s += *(const f32x4*)(ACC1 + ((size_t)kp * TS + srow) * N1 + col);
;     return s;
; }
; __device__ __forceinline__ void attn_sample_item(const P& p, int wi, int lane) {
;     ...
;             else { const int nr = bs * 4 + (idx - 2048); const float rsn = rstd1[TP + nr]; const int c0 = 4096 + h * 128 + 8 * li;
;                 k0 = acc1_4(ACC1, nr, c0) * rsn; k1 = acc1_4(ACC1, nr, c0 + 4) * rsn; v0 = acc1_4(ACC1, nr, c0 + 1024) * rsn; v1 = acc1_4(ACC1, nr, c0 + 1028) * rsn; }
	v_add_f32_e32 v176, v0, v4
	v_add_f32_e32 v177, v1, v5
	v_add_f32_e32 v178, v2, v6
	v_add_f32_e32 v179, v3, v7
	v_add_f32_e32 v176, v176, v8
	v_add_f32_e32 v177, v177, v9
	v_add_f32_e32 v178, v178, v10
	v_add_f32_e32 v179, v179, v11
	v_add_f32_e32 v176, v176, v12
	v_add_f32_e32 v177, v177, v13
	v_add_f32_e32 v178, v178, v14
	v_add_f32_e32 v179, v179, v15
	v_add_f32_e32 v176, v176, v16
	v_add_f32_e32 v177, v177, v17
	v_add_f32_e32 v178, v178, v18
	v_add_f32_e32 v179, v179, v19
	v_add_f32_e32 v176, v176, v20
	v_add_f32_e32 v177, v177, v21
	v_add_f32_e32 v178, v178, v22
	v_add_f32_e32 v179, v179, v23
	v_add_f32_e32 v176, v176, v24
	v_add_f32_e32 v177, v177, v25
	v_add_f32_e32 v178, v178, v26
	v_add_f32_e32 v179, v179, v27
	v_add_f32_e32 v176, v176, v28
	v_add_f32_e32 v177, v177, v29
	v_add_f32_e32 v178, v178, v30
	v_add_f32_e32 v179, v179, v31
	v_add_u32_e32 v71, 0x1000, v65
	global_load_dwordx4 v[0:3], v71, s[8:9]
	v_add_u32_e32 v71, 0x300000, v71
	global_load_dwordx4 v[4:7], v71, s[8:9]
	v_add_u32_e32 v71, 0x300000, v71
	global_load_dwordx4 v[8:11], v71, s[8:9]
	v_add_u32_e32 v71, 0x300000, v71
	global_load_dwordx4 v[12:15], v71, s[8:9]
	v_add_u32_e32 v71, 0x300000, v71
	global_load_dwordx4 v[16:19], v71, s[8:9]
	v_add_u32_e32 v71, 0x300000, v71
	global_load_dwordx4 v[20:23], v71, s[8:9]
	v_add_u32_e32 v71, 0x300000, v71
	global_load_dwordx4 v[24:27], v71, s[8:9]
	v_add_u32_e32 v71, 0x300000, v71
	global_load_dwordx4 v[28:31], v71, s[8:9]
	s_waitcnt vmcnt(8)
	v_add_f32_e32 v180, v32, v36
	v_add_f32_e32 v181, v33, v37
	v_add_f32_e32 v182, v34, v38
	v_add_f32_e32 v183, v35, v39
	v_add_f32_e32 v180, v180, v40
	v_add_f32_e32 v181, v181, v41
	v_add_f32_e32 v182, v182, v42
	v_add_f32_e32 v183, v183, v43
	v_add_f32_e32 v180, v180, v44
	v_add_f32_e32 v181, v181, v45
	v_add_f32_e32 v182, v182, v46
	v_add_f32_e32 v183, v183, v47
	v_add_f32_e32 v180, v180, v48
	v_add_f32_e32 v181, v181, v49
	v_add_f32_e32 v182, v182, v50
	v_add_f32_e32 v183, v183, v51
	v_add_f32_e32 v180, v180, v52
	v_add_f32_e32 v181, v181, v53
	v_add_f32_e32 v182, v182, v54
	v_add_f32_e32 v183, v183, v55
	v_add_f32_e32 v180, v180, v56
	v_add_f32_e32 v181, v181, v57
	v_add_f32_e32 v182, v182, v58
	v_add_f32_e32 v183, v183, v59
	v_add_f32_e32 v180, v180, v60
	v_add_f32_e32 v181, v181, v61
	v_add_f32_e32 v182, v182, v62
	v_add_f32_e32 v183, v183, v63
	v_add_u32_e32 v71, 0x1000, v65
	global_load_dwordx4 v[32:35], v71, s[8:9] offset:16
	v_add_u32_e32 v71, 0x300000, v71
	global_load_dwordx4 v[36:39], v71, s[8:9] offset:16
	v_add_u32_e32 v71, 0x300000, v71
	global_load_dwordx4 v[40:43], v71, s[8:9] offset:16
	v_add_u32_e32 v71, 0x300000, v71
	global_load_dwordx4 v[44:47], v71, s[8:9] offset:16
	v_add_u32_e32 v71, 0x300000, v71
	global_load_dwordx4 v[48:51], v71, s[8:9] offset:16
	v_add_u32_e32 v71, 0x300000, v71
	global_load_dwordx4 v[52:55], v71, s[8:9] offset:16
	v_add_u32_e32 v71, 0x300000, v71
	global_load_dwordx4 v[56:59], v71, s[8:9] offset:16
	v_add_u32_e32 v71, 0x300000, v71
	global_load_dwordx4 v[60:63], v71, s[8:9] offset:16
	s_waitcnt vmcnt(8)
	v_add_f32_e32 v184, v0, v4
	v_add_f32_e32 v185, v1, v5
	v_add_f32_e32 v186, v2, v6
	v_add_f32_e32 v187, v3, v7
	v_add_f32_e32 v184, v184, v8
	v_add_f32_e32 v185, v185, v9
	v_add_f32_e32 v186, v186, v10
	v_add_f32_e32 v187, v187, v11
	v_add_f32_e32 v184, v184, v12
	v_add_f32_e32 v185, v185, v13
	v_add_f32_e32 v186, v186, v14
	v_add_f32_e32 v187, v187, v15
	v_add_f32_e32 v184, v184, v16
	v_add_f32_e32 v185, v185, v17
	v_add_f32_e32 v186, v186, v18
	v_add_f32_e32 v187, v187, v19
	v_add_f32_e32 v184, v184, v20
	v_add_f32_e32 v185, v185, v21
	v_add_f32_e32 v186, v186, v22
	v_add_f32_e32 v187, v187, v23
	v_add_f32_e32 v184, v184, v24
	v_add_f32_e32 v185, v185, v25
	v_add_f32_e32 v186, v186, v26
	v_add_f32_e32 v187, v187, v27
	v_add_f32_e32 v184, v184, v28
	v_add_f32_e32 v185, v185, v29
	v_add_f32_e32 v186, v186, v30
	v_add_f32_e32 v187, v187, v31
	s_waitcnt vmcnt(0)
	v_add_f32_e32 v188, v32, v36
	v_add_f32_e32 v189, v33, v37
	v_add_f32_e32 v190, v34, v38
	v_add_f32_e32 v191, v35, v39
	v_add_f32_e32 v188, v188, v40
	v_add_f32_e32 v189, v189, v41
	v_add_f32_e32 v190, v190, v42
	v_add_f32_e32 v191, v191, v43
	v_add_f32_e32 v188, v188, v44
	v_add_f32_e32 v189, v189, v45
	v_add_f32_e32 v190, v190, v46
	v_add_f32_e32 v191, v191, v47
	v_add_f32_e32 v188, v188, v48
	v_add_f32_e32 v189, v189, v49
	v_add_f32_e32 v190, v190, v50
	v_add_f32_e32 v191, v191, v51
	v_add_f32_e32 v188, v188, v52
	v_add_f32_e32 v189, v189, v53
	v_add_f32_e32 v190, v190, v54
	v_add_f32_e32 v191, v191, v55
	v_add_f32_e32 v188, v188, v56
	v_add_f32_e32 v189, v189, v57
	v_add_f32_e32 v190, v190, v58
	v_add_f32_e32 v191, v191, v59
	v_add_f32_e32 v188, v188, v60
	v_add_f32_e32 v189, v189, v61
	v_add_f32_e32 v190, v190, v62
	v_add_f32_e32 v191, v191, v63
	s_waitcnt lgkmcnt(0)
; __device__ __forceinline__ float fexp2(float x) { return __builtin_amdgcn_exp2f(x); }
; __device__ __forceinline__ void attn_sample_item(const P& p, int wi, int lane) {
;     ...
;     { const float rq = rstd1[TP + srow] * (0.08838834764831845f * LOG2E);
;       const f32x4 q0 = acc1_4(ACC1, srow, 3072 + h * 128 + 8 * li), q1 = acc1_4(ACC1, srow, 3072 + h * 128 + 8 * li + 4);
;       q[0] = q0[0] * rq; q[1] = q0[1] * rq; q[2] = q0[2] * rq; q[3] = q0[3] * rq; q[4] = q1[0] * rq; q[5] = q1[1] * rq; q[6] = q1[2] * rq; q[7] = q1[3] * rq; }
;     if (kg == 0) {
;         const float rs = rstd1[TP + srow];
;         float* ko = p.out + OUT_KN + (size_t)srow * 1024 + h * 128 + 8 * li; float* vo = p.out + OUT_VN + (size_t)srow * 1024 + h * 128 + 8 * li;
;         *(f32x4*)ko = acc1_4(ACC1, srow, 4096 + h * 128 + 8 * li) * rs; *(f32x4*)(ko + 4) = acc1_4(ACC1, srow, 4096 + h * 128 + 8 * li + 4) * rs;
;         *(f32x4*)vo = acc1_4(ACC1, srow, 5120 + h * 128 + 8 * li) * rs; *(f32x4*)(vo + 4) = acc1_4(ACC1, srow, 5120 + h * 128 + 8 * li + 4) * rs;
;     }
;     float m = -1e30f, l = 0.f, acc[8];
; #pragma unroll
;     for (int e = 0; e < 8; ++e) acc[e] = 0.f;
;     const float sl = fexp2(-(float)(h + 1)) * LOG2E;
;     for (int g = 0; g < 3; ++g) {
;         const int d = 1 << (2 * g);
; #pragma unroll 3
;         for (int jj = 0; jj < 33; ++jj) {
;             const int j = 4 * jj + kg; const bool valid = j <= 128; const int jc = valid ? j : 128;
;             const int idx = 2048 + i - d * jc;
;             f32x4 k0, k1, v0, v1;
;             if (idx < 2048) { const size_t off = (((size_t)bs * 2048 + idx) * 8 + h) * 128 + 8 * li;
;                 k0 = __builtin_nontemporal_load((const f32x4*)(p.cache_k + off)); k1 = __builtin_nontemporal_load((const f32x4*)(p.cache_k + off + 4)); v0 = __builtin_nontemporal_load((const f32x4*)(p.cache_v + off)); v1 = __builtin_nontemporal_load((const f32x4*)(p.cache_v + off + 4)); }
;             else { const int nr = bs * 4 + (idx - 2048); const float rsn = rstd1[TP + nr]; const int c0 = 4096 + h * 128 + 8 * li;
;                 k0 = acc1_4(ACC1, nr, c0) * rsn; k1 = acc1_4(ACC1, nr, c0 + 4) * rsn; v0 = acc1_4(ACC1, nr, c0 + 1024) * rsn; v1 = acc1_4(ACC1, nr, c0 + 1028) * rsn; }
;             float dot = (q[0] * k0[0] + q[1] * k0[1]) + (q[2] * k0[2] + q[3] * k0[3]) + (q[4] * k1[0] + q[5] * k1[1]) + (q[6] * k1[2] + q[7] * k1[3]);
	v_mov_b32_e32 v71, s19
	v_mul_f32_e32 v71, 0x3e0293ee, v71
	v_mul_f32_e32 v160, v160, v71
	v_mul_f32_e32 v161, v161, v71
	v_mul_f32_e32 v162, v162, v71
	v_mul_f32_e32 v163, v163, v71
	v_mul_f32_e32 v164, v164, v71
	v_mul_f32_e32 v165, v165, v71
	v_mul_f32_e32 v166, v166, v71
	v_mul_f32_e32 v167, v167, v71
	v_mul_f32_e32 v176, v176, v70
	v_mul_f32_e32 v177, v177, v70
	v_mul_f32_e32 v178, v178, v70
	v_mul_f32_e32 v179, v179, v70
	v_mul_f32_e32 v180, v180, v70
	v_mul_f32_e32 v181, v181, v70
	v_mul_f32_e32 v182, v182, v70
	v_mul_f32_e32 v183, v183, v70
	v_mul_f32_e32 v184, v184, v70
	v_mul_f32_e32 v185, v185, v70
	v_mul_f32_e32 v186, v186, v70
	v_mul_f32_e32 v187, v187, v70
	v_mul_f32_e32 v188, v188, v70
	v_mul_f32_e32 v189, v189, v70
	v_mul_f32_e32 v190, v190, v70
	v_mul_f32_e32 v191, v191, v70
	s_lshl_b32 s43, s17, 12
	v_add_u32_e32 v71, s43, v72
	s_mov_b64 exec, 0xffff
	global_store_dwordx4 v71, v[176:179], s[26:27]
	global_store_dwordx4 v71, v[180:183], s[26:27] offset:16
	global_store_dwordx4 v71, v[184:187], s[28:29]
	global_store_dwordx4 v71, v[188:191], s[28:29] offset:16
	s_mov_b64 exec, -1
	v_cmp_ge_u32_e32 vcc, s15, v73
	s_nop 1
	v_cndmask_b32_e32 v128, v128, v176, vcc
	v_cndmask_b32_e32 v129, v129, v177, vcc
	v_cndmask_b32_e32 v130, v130, v178, vcc
	v_cndmask_b32_e32 v131, v131, v179, vcc
	v_cndmask_b32_e32 v132, v132, v180, vcc
	v_cndmask_b32_e32 v133, v133, v181, vcc
	v_cndmask_b32_e32 v134, v134, v182, vcc
	v_cndmask_b32_e32 v135, v135, v183, vcc
	v_cndmask_b32_e32 v136, v136, v184, vcc
	v_cndmask_b32_e32 v137, v137, v185, vcc
	v_cndmask_b32_e32 v138, v138, v186, vcc
	v_cndmask_b32_e32 v139, v139, v187, vcc
	v_cndmask_b32_e32 v140, v140, v188, vcc
	v_cndmask_b32_e32 v141, v141, v189, vcc
	v_cndmask_b32_e32 v142, v142, v190, vcc
	v_cndmask_b32_e32 v143, v143, v191, vcc
	v_bfe_u32 v183, v230, 4, 2
	v_lshlrev_b32_e32 v195, 12, v183
	v_sub_u32_e32 v195, v203, v195
	s_mov_b32 s42, 0xffffc000
	v_add_u32_e32 v195, s42, v195
	global_load_dwordx4 v[16:19], v195, s[20:21]
	global_load_dwordx4 v[20:23], v195, s[20:21] offset:16
	global_load_dwordx4 v[24:27], v195, s[24:25]
	global_load_dwordx4 v[28:31], v195, s[24:25] offset:16
	v_add_u32_e32 v195, s42, v195
	global_load_dwordx4 v[32:35], v195, s[20:21]
	global_load_dwordx4 v[36:39], v195, s[20:21] offset:16
	global_load_dwordx4 v[40:43], v195, s[24:25]
	global_load_dwordx4 v[44:47], v195, s[24:25] offset:16
	v_add_u32_e32 v195, s42, v195
	global_load_dwordx4 v[48:51], v195, s[20:21]
	global_load_dwordx4 v[52:55], v195, s[20:21] offset:16
	global_load_dwordx4 v[56:59], v195, s[24:25]
	global_load_dwordx4 v[60:63], v195, s[24:25] offset:16
	v_add_u32_e32 v195, s42, v195
	global_load_dwordx4 v[64:67], v195, s[20:21]
	global_load_dwordx4 v[68:71], v195, s[20:21] offset:16
	global_load_dwordx4 v[72:75], v195, s[24:25]
	global_load_dwordx4 v[76:79], v195, s[24:25] offset:16
	v_add_u32_e32 v195, s42, v195
	global_load_dwordx4 v[80:83], v195, s[20:21]
	global_load_dwordx4 v[84:87], v195, s[20:21] offset:16
	global_load_dwordx4 v[88:91], v195, s[24:25]
	global_load_dwordx4 v[92:95], v195, s[24:25] offset:16
	v_add_u32_e32 v195, s42, v195
	global_load_dwordx4 v[96:99], v195, s[20:21]
	global_load_dwordx4 v[100:103], v195, s[20:21] offset:16
	global_load_dwordx4 v[104:107], v195, s[24:25]
	global_load_dwordx4 v[108:111], v195, s[24:25] offset:16
	v_add_u32_e32 v195, s42, v195
	global_load_dwordx4 v[112:115], v195, s[20:21]
	global_load_dwordx4 v[116:119], v195, s[20:21] offset:16
	global_load_dwordx4 v[120:123], v195, s[24:25]
	global_load_dwordx4 v[124:127], v195, s[24:25] offset:16
	v_add_u32_e32 v195, s42, v195
	global_load_dwordx4 v[0:3], v195, s[20:21]
	global_load_dwordx4 v[4:7], v195, s[20:21] offset:16
	global_load_dwordx4 v[8:11], v195, s[24:25]
	global_load_dwordx4 v[12:15], v195, s[24:25] offset:16
	v_lshlrev_b32_e32 v176, 14, v183
	v_sub_u32_e32 v176, v203, v176
	v_add_u32_e32 v176, 0xc000, v176
	v_lshlrev_b32_e32 v177, 16, v183
	v_sub_u32_e32 v177, v203, v177
	v_add_u32_e32 v177, 0x30000, v177
	v_add_f32_e32 v182, 1.0, v202
	v_mul_f32_e32 v182, v182, v201
	v_mul_f32_e32 v178, 4.0, v182
	v_mul_f32_e32 v179, 16.0, v182
	v_mul_f32_e32 v180, 16.0, v201
	v_mul_f32_e32 v181, 64.0, v201
	v_mul_f32_e32 v196, 4.0, v201
	v_mov_b32_e32 v192, 0xf149f2ca
	v_mov_b32_e32 v193, 0
	v_mov_b32_e32 v168, 0
	v_mov_b32_e32 v169, 0
	v_mov_b32_e32 v170, 0
	v_mov_b32_e32 v171, 0
	v_mov_b32_e32 v172, 0
	v_mov_b32_e32 v173, 0
	v_mov_b32_e32 v174, 0
	v_mov_b32_e32 v175, 0
	v_mul_f32_e32 v194, v201, v202
	v_mov_b32_e32 v182, 0x3dcae00d
	v_cmp_eq_u32_e32 vcc, 0, v183
	s_nop 1
	v_cndmask_b32_e32 v194, v194, v182, vcc
	v_fma_f32 v197, v160, v128, v194
	v_fmac_f32_e32 v197, v161, v129
	v_fmac_f32_e32 v197, v162, v130
	v_fmac_f32_e32 v197, v163, v131
	v_fmac_f32_e32 v197, v164, v132
	v_fmac_f32_e32 v197, v165, v133
	v_fmac_f32_e32 v197, v166, v134
	v_fmac_f32_e32 v197, v167, v135
	s_nop 1
	v_add_f32_dpp v197, v197, v197 row_ror:8 row_mask:0xf bank_mask:0xf
	s_nop 1
	v_add_f32_dpp v197, v197, v197 row_ror:4 row_mask:0xf bank_mask:0xf
	s_nop 1
	v_add_f32_dpp v197, v197, v197 row_ror:2 row_mask:0xf bank_mask:0xf
	s_nop 1
	v_add_f32_dpp v197, v197, v197 row_ror:1 row_mask:0xf bank_mask:0xf
	v_max_f32_e32 v198, v192, v197
	v_sub_f32_e32 v199, v192, v198
	v_sub_f32_e32 v200, v197, v198
	v_exp_f32_e32 v199, v199
	v_exp_f32_e32 v200, v200
	v_mov_b32_e32 v192, v198
	v_fma_f32 v193, v193, v199, v200
	v_mul_f32_e32 v168, v168, v199
	v_mul_f32_e32 v169, v169, v199
	v_mul_f32_e32 v170, v170, v199
	v_mul_f32_e32 v171, v171, v199
	v_mul_f32_e32 v172, v172, v199
	v_mul_f32_e32 v173, v173, v199
	v_mul_f32_e32 v174, v174, v199
; __device__ __forceinline__ float fexp2(float x) { return __builtin_amdgcn_exp2f(x); }
; __device__ __forceinline__ void attn_sample_item(const P& p, int wi, int lane) {
;     ...
;     for (int g = 0; g < 3; ++g) {
;         const int d = 1 << (2 * g);
; #pragma unroll 3
;         for (int jj = 0; jj < 33; ++jj) {
;             const int j = 4 * jj + kg; const bool valid = j <= 128; const int jc = valid ? j : 128;
;             const int idx = 2048 + i - d * jc;
;             f32x4 k0, k1, v0, v1;
;             if (idx < 2048) { const size_t off = (((size_t)bs * 2048 + idx) * 8 + h) * 128 + 8 * li;
;                 k0 = __builtin_nontemporal_load((const f32x4*)(p.cache_k + off)); k1 = __builtin_nontemporal_load((const f32x4*)(p.cache_k + off + 4)); v0 = __builtin_nontemporal_load((const f32x4*)(p.cache_v + off)); v1 = __builtin_nontemporal_load((const f32x4*)(p.cache_v + off + 4)); }
;             else { const int nr = bs * 4 + (idx - 2048); const float rsn = rstd1[TP + nr]; const int c0 = 4096 + h * 128 + 8 * li;
;                 k0 = acc1_4(ACC1, nr, c0) * rsn; k1 = acc1_4(ACC1, nr, c0 + 4) * rsn; v0 = acc1_4(ACC1, nr, c0 + 1024) * rsn; v1 = acc1_4(ACC1, nr, c0 + 1028) * rsn; }
;             float dot = (q[0] * k0[0] + q[1] * k0[1]) + (q[2] * k0[2] + q[3] * k0[3]) + (q[4] * k1[0] + q[5] * k1[1]) + (q[6] * k1[2] + q[7] * k1[3]);
;             dot += __shfl_xor(dot, 1); dot += __shfl_xor(dot, 2); dot += __shfl_xor(dot, 4); dot += __shfl_xor(dot, 8);
;             const float s = valid ? dot - sl * (float)(d * j) : -INFINITY;
;             const float mn = fmaxf(m, s), sc = fexp2(m - mn), pe = fexp2(s - mn);
;             l = l * sc + pe;
;             acc[0] = acc[0] * sc + pe * v0[0]; acc[1] = acc[1] * sc + pe * v0[1]; acc[2] = acc[2] * sc + pe * v0[2]; acc[3] = acc[3] * sc + pe * v0[3];
;             acc[4] = acc[4] * sc + pe * v1[0]; acc[5] = acc[5] * sc + pe * v1[1]; acc[6] = acc[6] * sc + pe * v1[2]; acc[7] = acc[7] * sc + pe * v1[3];
;             m = mn;
;         }
	v_mul_f32_e32 v175, v175, v199
	v_fmac_f32_e32 v168, v200, v136
	v_fmac_f32_e32 v169, v200, v137
	v_fmac_f32_e32 v170, v200, v138
	v_fmac_f32_e32 v171, v200, v139
	v_fmac_f32_e32 v172, v200, v140
	v_fmac_f32_e32 v173, v200, v141
	v_fmac_f32_e32 v174, v200, v142
	v_fmac_f32_e32 v175, v200, v143
	v_mul_f32_e32 v194, 0x43000000, v201
	v_mov_b32_e32 v182, 0xff800000
	v_cndmask_b32_e32 v194, v182, v194, vcc
	v_fma_f32 v197, v160, v144, v194
	v_fmac_f32_e32 v197, v161, v145
	v_fmac_f32_e32 v197, v162, v146
	v_fmac_f32_e32 v197, v163, v147
	v_fmac_f32_e32 v197, v164, v148
	v_fmac_f32_e32 v197, v165, v149
	v_fmac_f32_e32 v197, v166, v150
	v_fmac_f32_e32 v197, v167, v151
	s_nop 1
	v_add_f32_dpp v197, v197, v197 row_ror:8 row_mask:0xf bank_mask:0xf
	s_nop 1
	v_add_f32_dpp v197, v197, v197 row_ror:4 row_mask:0xf bank_mask:0xf
	s_nop 1
	v_add_f32_dpp v197, v197, v197 row_ror:2 row_mask:0xf bank_mask:0xf
	s_nop 1
	v_add_f32_dpp v197, v197, v197 row_ror:1 row_mask:0xf bank_mask:0xf
	v_max_f32_e32 v198, v192, v197
	v_sub_f32_e32 v199, v192, v198
	v_sub_f32_e32 v200, v197, v198
	v_exp_f32_e32 v199, v199
	v_exp_f32_e32 v200, v200
	v_mov_b32_e32 v192, v198
	v_fma_f32 v193, v193, v199, v200
	v_mul_f32_e32 v168, v168, v199
	v_mul_f32_e32 v169, v169, v199
	v_mul_f32_e32 v170, v170, v199
	v_mul_f32_e32 v171, v171, v199
	v_mul_f32_e32 v172, v172, v199
	v_mul_f32_e32 v173, v173, v199
	v_mul_f32_e32 v174, v174, v199
	v_mul_f32_e32 v175, v175, v199
	v_fmac_f32_e32 v168, v200, v152
	v_fmac_f32_e32 v169, v200, v153
	v_fmac_f32_e32 v170, v200, v154
	v_fmac_f32_e32 v171, v200, v155
	v_fmac_f32_e32 v172, v200, v156
	v_fmac_f32_e32 v173, v200, v157
	v_fmac_f32_e32 v174, v200, v158
	v_fmac_f32_e32 v175, v200, v159
	v_add_f32_e32 v194, 4.0, v202
	v_mul_f32_e32 v194, v194, v201
	s_mov_b32 s33, 0
	s_branch .Las_slot1
.Las_trip:
	s_cmp_eq_u32 s33, 3
	s_cbranch_scc0 .Las_sw1
	v_mov_b32_e32 v195, v176
	s_mov_b32 s42, 0xffff0000
.Las_sw1:
	s_cmp_eq_u32 s33, 7
	s_cbranch_scc0 .Las_sw2
	v_mov_b32_e32 v195, v177
	s_mov_b32 s42, 0xfffc0000
.Las_sw2:
	s_cmp_eq_u32 s33, 4
	s_cbranch_scc0 .Las_sw3
	v_mov_b32_e32 v194, v178
	v_mov_b32_e32 v196, v180
.Las_sw3:
	s_cmp_eq_u32 s33, 8
	s_cbranch_scc0 .Las_sw4
	v_mov_b32_e32 v194, v179
	v_mov_b32_e32 v196, v181
.Las_sw4:
	s_waitcnt vmcnt(28)
	v_fma_f32 v197, v160, v0, v194
	v_fmac_f32_e32 v197, v161, v1
	v_fmac_f32_e32 v197, v162, v2
	v_fmac_f32_e32 v197, v163, v3
	v_fmac_f32_e32 v197, v164, v4
	v_fmac_f32_e32 v197, v165, v5
	v_fmac_f32_e32 v197, v166, v6
	v_fmac_f32_e32 v197, v167, v7
	s_nop 1
	v_add_f32_dpp v197, v197, v197 row_ror:8 row_mask:0xf bank_mask:0xf
	s_nop 1
	v_add_f32_dpp v197, v197, v197 row_ror:4 row_mask:0xf bank_mask:0xf
	s_nop 1
	v_add_f32_dpp v197, v197, v197 row_ror:2 row_mask:0xf bank_mask:0xf
	s_nop 1
	v_add_f32_dpp v197, v197, v197 row_ror:1 row_mask:0xf bank_mask:0xf
	v_max_f32_e32 v198, v192, v197
	v_sub_f32_e32 v199, v192, v198
	v_sub_f32_e32 v200, v197, v198
	v_exp_f32_e32 v199, v199
	v_exp_f32_e32 v200, v200
	v_mov_b32_e32 v192, v198
	v_fma_f32 v193, v193, v199, v200
	v_mul_f32_e32 v168, v168, v199
	v_mul_f32_e32 v169, v169, v199
	v_mul_f32_e32 v170, v170, v199
	v_mul_f32_e32 v171, v171, v199
	v_mul_f32_e32 v172, v172, v199
	v_mul_f32_e32 v173, v173, v199
	v_mul_f32_e32 v174, v174, v199
	v_mul_f32_e32 v175, v175, v199
	v_fmac_f32_e32 v168, v200, v8
	v_fmac_f32_e32 v169, v200, v9
	v_fmac_f32_e32 v170, v200, v10
	v_fmac_f32_e32 v171, v200, v11
	v_fmac_f32_e32 v172, v200, v12
	v_fmac_f32_e32 v173, v200, v13
	v_fmac_f32_e32 v174, v200, v14
	v_fmac_f32_e32 v175, v200, v15
	v_add_f32_e32 v194, v194, v196
	v_add_u32_e32 v195, s42, v195
	global_load_dwordx4 v[0:3], v195, s[20:21] nt
	global_load_dwordx4 v[4:7], v195, s[20:21] offset:16 nt
	global_load_dwordx4 v[8:11], v195, s[24:25] nt
	global_load_dwordx4 v[12:15], v195, s[24:25] offset:16 nt
.Las_slot1:
	s_waitcnt vmcnt(28)
	v_fma_f32 v197, v160, v16, v194
	v_fmac_f32_e32 v197, v161, v17
	v_fmac_f32_e32 v197, v162, v18
	v_fmac_f32_e32 v197, v163, v19
	v_fmac_f32_e32 v197, v164, v20
	v_fmac_f32_e32 v197, v165, v21
	v_fmac_f32_e32 v197, v166, v22
	v_fmac_f32_e32 v197, v167, v23
	s_nop 1
	v_add_f32_dpp v197, v197, v197 row_ror:8 row_mask:0xf bank_mask:0xf
	s_nop 1
	v_add_f32_dpp v197, v197, v197 row_ror:4 row_mask:0xf bank_mask:0xf
	s_nop 1
	v_add_f32_dpp v197, v197, v197 row_ror:2 row_mask:0xf bank_mask:0xf
	s_nop 1
	v_add_f32_dpp v197, v197, v197 row_ror:1 row_mask:0xf bank_mask:0xf
	v_max_f32_e32 v198, v192, v197
	v_sub_f32_e32 v199, v192, v198
	v_sub_f32_e32 v200, v197, v198
	v_exp_f32_e32 v199, v199
	v_exp_f32_e32 v200, v200
	v_mov_b32_e32 v192, v198
	v_fma_f32 v193, v193, v199, v200
	v_mul_f32_e32 v168, v168, v199
	v_mul_f32_e32 v169, v169, v199
	v_mul_f32_e32 v170, v170, v199
	v_mul_f32_e32 v171, v171, v199
	v_mul_f32_e32 v172, v172, v199
	v_mul_f32_e32 v173, v173, v199
	v_mul_f32_e32 v174, v174, v199
	v_mul_f32_e32 v175, v175, v199
	v_fmac_f32_e32 v168, v200, v24
	v_fmac_f32_e32 v169, v200, v25
	v_fmac_f32_e32 v170, v200, v26
	v_fmac_f32_e32 v171, v200, v27
	v_fmac_f32_e32 v172, v200, v28
	v_fmac_f32_e32 v173, v200, v29
	v_fmac_f32_e32 v174, v200, v30
	v_fmac_f32_e32 v175, v200, v31
	v_add_f32_e32 v194, v194, v196
	v_add_u32_e32 v195, s42, v195
	global_load_dwordx4 v[16:19], v195, s[20:21] nt
	global_load_dwordx4 v[20:23], v195, s[20:21] offset:16 nt
	global_load_dwordx4 v[24:27], v195, s[24:25] nt
	global_load_dwordx4 v[28:31], v195, s[24:25] offset:16 nt
	s_waitcnt vmcnt(28)
; __device__ __forceinline__ float fexp2(float x) { return __builtin_amdgcn_exp2f(x); }
; __device__ __forceinline__ void attn_sample_item(const P& p, int wi, int lane) {
;     ...
;         for (int jj = 0; jj < 33; ++jj) {
;             const int j = 4 * jj + kg; const bool valid = j <= 128; const int jc = valid ? j : 128;
;             const int idx = 2048 + i - d * jc;
;             f32x4 k0, k1, v0, v1;
;             if (idx < 2048) { const size_t off = (((size_t)bs * 2048 + idx) * 8 + h) * 128 + 8 * li;
;                 k0 = __builtin_nontemporal_load((const f32x4*)(p.cache_k + off)); k1 = __builtin_nontemporal_load((const f32x4*)(p.cache_k + off + 4)); v0 = __builtin_nontemporal_load((const f32x4*)(p.cache_v + off)); v1 = __builtin_nontemporal_load((const f32x4*)(p.cache_v + off + 4)); }
;             else { const int nr = bs * 4 + (idx - 2048); const float rsn = rstd1[TP + nr]; const int c0 = 4096 + h * 128 + 8 * li;
;                 k0 = acc1_4(ACC1, nr, c0) * rsn; k1 = acc1_4(ACC1, nr, c0 + 4) * rsn; v0 = acc1_4(ACC1, nr, c0 + 1024) * rsn; v1 = acc1_4(ACC1, nr, c0 + 1028) * rsn; }
;             float dot = (q[0] * k0[0] + q[1] * k0[1]) + (q[2] * k0[2] + q[3] * k0[3]) + (q[4] * k1[0] + q[5] * k1[1]) + (q[6] * k1[2] + q[7] * k1[3]);
;             dot += __shfl_xor(dot, 1); dot += __shfl_xor(dot, 2); dot += __shfl_xor(dot, 4); dot += __shfl_xor(dot, 8);
;             const float s = valid ? dot - sl * (float)(d * j) : -INFINITY;
;             const float mn = fmaxf(m, s), sc = fexp2(m - mn), pe = fexp2(s - mn);
;             l = l * sc + pe;
;             acc[0] = acc[0] * sc + pe * v0[0]; acc[1] = acc[1] * sc + pe * v0[1]; acc[2] = acc[2] * sc + pe * v0[2]; acc[3] = acc[3] * sc + pe * v0[3];
;             acc[4] = acc[4] * sc + pe * v1[0]; acc[5] = acc[5] * sc + pe * v1[1]; acc[6] = acc[6] * sc + pe * v1[2]; acc[7] = acc[7] * sc + pe * v1[3];
;             m = mn;
;         }
	v_fma_f32 v197, v160, v32, v194
	v_fmac_f32_e32 v197, v161, v33
	v_fmac_f32_e32 v197, v162, v34
	v_fmac_f32_e32 v197, v163, v35
	v_fmac_f32_e32 v197, v164, v36
	v_fmac_f32_e32 v197, v165, v37
	v_fmac_f32_e32 v197, v166, v38
	v_fmac_f32_e32 v197, v167, v39
	s_nop 1
	v_add_f32_dpp v197, v197, v197 row_ror:8 row_mask:0xf bank_mask:0xf
	s_nop 1
	v_add_f32_dpp v197, v197, v197 row_ror:4 row_mask:0xf bank_mask:0xf
	s_nop 1
	v_add_f32_dpp v197, v197, v197 row_ror:2 row_mask:0xf bank_mask:0xf
	s_nop 1
	v_add_f32_dpp v197, v197, v197 row_ror:1 row_mask:0xf bank_mask:0xf
	v_max_f32_e32 v198, v192, v197
	v_sub_f32_e32 v199, v192, v198
	v_sub_f32_e32 v200, v197, v198
	v_exp_f32_e32 v199, v199
	v_exp_f32_e32 v200, v200
	v_mov_b32_e32 v192, v198
	v_fma_f32 v193, v193, v199, v200
	v_mul_f32_e32 v168, v168, v199
	v_mul_f32_e32 v169, v169, v199
	v_mul_f32_e32 v170, v170, v199
	v_mul_f32_e32 v171, v171, v199
	v_mul_f32_e32 v172, v172, v199
	v_mul_f32_e32 v173, v173, v199
	v_mul_f32_e32 v174, v174, v199
	v_mul_f32_e32 v175, v175, v199
	v_fmac_f32_e32 v168, v200, v40
	v_fmac_f32_e32 v169, v200, v41
	v_fmac_f32_e32 v170, v200, v42
	v_fmac_f32_e32 v171, v200, v43
	v_fmac_f32_e32 v172, v200, v44
	v_fmac_f32_e32 v173, v200, v45
	v_fmac_f32_e32 v174, v200, v46
	v_fmac_f32_e32 v175, v200, v47
	v_add_f32_e32 v194, v194, v196
	v_add_u32_e32 v195, s42, v195
	global_load_dwordx4 v[32:35], v195, s[20:21] nt
	global_load_dwordx4 v[36:39], v195, s[20:21] offset:16 nt
	global_load_dwordx4 v[40:43], v195, s[24:25] nt
	global_load_dwordx4 v[44:47], v195, s[24:25] offset:16 nt
	s_waitcnt vmcnt(28)
	v_fma_f32 v197, v160, v48, v194
	v_fmac_f32_e32 v197, v161, v49
	v_fmac_f32_e32 v197, v162, v50
	v_fmac_f32_e32 v197, v163, v51
	v_fmac_f32_e32 v197, v164, v52
	v_fmac_f32_e32 v197, v165, v53
	v_fmac_f32_e32 v197, v166, v54
	v_fmac_f32_e32 v197, v167, v55
	s_nop 1
	v_add_f32_dpp v197, v197, v197 row_ror:8 row_mask:0xf bank_mask:0xf
	s_nop 1
	v_add_f32_dpp v197, v197, v197 row_ror:4 row_mask:0xf bank_mask:0xf
	s_nop 1
	v_add_f32_dpp v197, v197, v197 row_ror:2 row_mask:0xf bank_mask:0xf
	s_nop 1
	v_add_f32_dpp v197, v197, v197 row_ror:1 row_mask:0xf bank_mask:0xf
	v_max_f32_e32 v198, v192, v197
	v_sub_f32_e32 v199, v192, v198
	v_sub_f32_e32 v200, v197, v198
	v_exp_f32_e32 v199, v199
	v_exp_f32_e32 v200, v200
	v_mov_b32_e32 v192, v198
	v_fma_f32 v193, v193, v199, v200
	v_mul_f32_e32 v168, v168, v199
	v_mul_f32_e32 v169, v169, v199
	v_mul_f32_e32 v170, v170, v199
	v_mul_f32_e32 v171, v171, v199
	v_mul_f32_e32 v172, v172, v199
	v_mul_f32_e32 v173, v173, v199
	v_mul_f32_e32 v174, v174, v199
	v_mul_f32_e32 v175, v175, v199
	v_fmac_f32_e32 v168, v200, v56
	v_fmac_f32_e32 v169, v200, v57
	v_fmac_f32_e32 v170, v200, v58
	v_fmac_f32_e32 v171, v200, v59
	v_fmac_f32_e32 v172, v200, v60
	v_fmac_f32_e32 v173, v200, v61
	v_fmac_f32_e32 v174, v200, v62
	v_fmac_f32_e32 v175, v200, v63
	v_add_f32_e32 v194, v194, v196
	v_add_u32_e32 v195, s42, v195
	global_load_dwordx4 v[48:51], v195, s[20:21] nt
	global_load_dwordx4 v[52:55], v195, s[20:21] offset:16 nt
	global_load_dwordx4 v[56:59], v195, s[24:25] nt
	global_load_dwordx4 v[60:63], v195, s[24:25] offset:16 nt
	s_waitcnt vmcnt(28)
	v_fma_f32 v197, v160, v64, v194
	v_fmac_f32_e32 v197, v161, v65
	v_fmac_f32_e32 v197, v162, v66
	v_fmac_f32_e32 v197, v163, v67
	v_fmac_f32_e32 v197, v164, v68
	v_fmac_f32_e32 v197, v165, v69
	v_fmac_f32_e32 v197, v166, v70
	v_fmac_f32_e32 v197, v167, v71
	s_nop 1
	v_add_f32_dpp v197, v197, v197 row_ror:8 row_mask:0xf bank_mask:0xf
	s_nop 1
	v_add_f32_dpp v197, v197, v197 row_ror:4 row_mask:0xf bank_mask:0xf
	s_nop 1
	v_add_f32_dpp v197, v197, v197 row_ror:2 row_mask:0xf bank_mask:0xf
	s_nop 1
	v_add_f32_dpp v197, v197, v197 row_ror:1 row_mask:0xf bank_mask:0xf
	v_max_f32_e32 v198, v192, v197
	v_sub_f32_e32 v199, v192, v198
	v_sub_f32_e32 v200, v197, v198
	v_exp_f32_e32 v199, v199
	v_exp_f32_e32 v200, v200
	v_mov_b32_e32 v192, v198
	v_fma_f32 v193, v193, v199, v200
	v_mul_f32_e32 v168, v168, v199
	v_mul_f32_e32 v169, v169, v199
	v_mul_f32_e32 v170, v170, v199
	v_mul_f32_e32 v171, v171, v199
	v_mul_f32_e32 v172, v172, v199
	v_mul_f32_e32 v173, v173, v199
	v_mul_f32_e32 v174, v174, v199
	v_mul_f32_e32 v175, v175, v199
	v_fmac_f32_e32 v168, v200, v72
	v_fmac_f32_e32 v169, v200, v73
	v_fmac_f32_e32 v170, v200, v74
	v_fmac_f32_e32 v171, v200, v75
	v_fmac_f32_e32 v172, v200, v76
	v_fmac_f32_e32 v173, v200, v77
	v_fmac_f32_e32 v174, v200, v78
	v_fmac_f32_e32 v175, v200, v79
	v_add_f32_e32 v194, v194, v196
	v_add_u32_e32 v195, s42, v195
	global_load_dwordx4 v[64:67], v195, s[20:21] nt
	global_load_dwordx4 v[68:71], v195, s[20:21] offset:16 nt
	global_load_dwordx4 v[72:75], v195, s[24:25] nt
	global_load_dwordx4 v[76:79], v195, s[24:25] offset:16 nt
	s_waitcnt vmcnt(28)
	v_fma_f32 v197, v160, v80, v194
	v_fmac_f32_e32 v197, v161, v81
	v_fmac_f32_e32 v197, v162, v82
	v_fmac_f32_e32 v197, v163, v83
	v_fmac_f32_e32 v197, v164, v84
	v_fmac_f32_e32 v197, v165, v85
	v_fmac_f32_e32 v197, v166, v86
	v_fmac_f32_e32 v197, v167, v87
	s_nop 1
	v_add_f32_dpp v197, v197, v197 row_ror:8 row_mask:0xf bank_mask:0xf
	s_nop 1
	v_add_f32_dpp v197, v197, v197 row_ror:4 row_mask:0xf bank_mask:0xf
	s_nop 1
	v_add_f32_dpp v197, v197, v197 row_ror:2 row_mask:0xf bank_mask:0xf
	s_nop 1
	v_add_f32_dpp v197, v197, v197 row_ror:1 row_mask:0xf bank_mask:0xf
	v_max_f32_e32 v198, v192, v197
	v_sub_f32_e32 v199, v192, v198
	v_sub_f32_e32 v200, v197, v198
	v_exp_f32_e32 v199, v199
	v_exp_f32_e32 v200, v200
	v_mov_b32_e32 v192, v198
	v_fma_f32 v193, v193, v199, v200
	v_mul_f32_e32 v168, v168, v199
	v_mul_f32_e32 v169, v169, v199
	v_mul_f32_e32 v170, v170, v199
	v_mul_f32_e32 v171, v171, v199
	v_mul_f32_e32 v172, v172, v199
	v_mul_f32_e32 v173, v173, v199
	v_mul_f32_e32 v174, v174, v199
	v_mul_f32_e32 v175, v175, v199
	v_fmac_f32_e32 v168, v200, v88
	v_fmac_f32_e32 v169, v200, v89
	v_fmac_f32_e32 v170, v200, v90
	v_fmac_f32_e32 v171, v200, v91
	v_fmac_f32_e32 v172, v200, v92
	v_fmac_f32_e32 v173, v200, v93
	v_fmac_f32_e32 v174, v200, v94
	v_fmac_f32_e32 v175, v200, v95
	v_add_f32_e32 v194, v194, v196
	v_add_u32_e32 v195, s42, v195
	global_load_dwordx4 v[80:83], v195, s[20:21] nt
	global_load_dwordx4 v[84:87], v195, s[20:21] offset:16 nt
	global_load_dwordx4 v[88:91], v195, s[24:25] nt
	global_load_dwordx4 v[92:95], v195, s[24:25] offset:16 nt
	s_waitcnt vmcnt(28)
; __device__ __forceinline__ float fexp2(float x) { return __builtin_amdgcn_exp2f(x); }
; __device__ __forceinline__ void attn_sample_item(const P& p, int wi, int lane) {
;     ...
;         for (int jj = 0; jj < 33; ++jj) {
;             const int j = 4 * jj + kg; const bool valid = j <= 128; const int jc = valid ? j : 128;
;             const int idx = 2048 + i - d * jc;
;             f32x4 k0, k1, v0, v1;
;             if (idx < 2048) { const size_t off = (((size_t)bs * 2048 + idx) * 8 + h) * 128 + 8 * li;
;                 k0 = __builtin_nontemporal_load((const f32x4*)(p.cache_k + off)); k1 = __builtin_nontemporal_load((const f32x4*)(p.cache_k + off + 4)); v0 = __builtin_nontemporal_load((const f32x4*)(p.cache_v + off)); v1 = __builtin_nontemporal_load((const f32x4*)(p.cache_v + off + 4)); }
;             else { const int nr = bs * 4 + (idx - 2048); const float rsn = rstd1[TP + nr]; const int c0 = 4096 + h * 128 + 8 * li;
;                 k0 = acc1_4(ACC1, nr, c0) * rsn; k1 = acc1_4(ACC1, nr, c0 + 4) * rsn; v0 = acc1_4(ACC1, nr, c0 + 1024) * rsn; v1 = acc1_4(ACC1, nr, c0 + 1028) * rsn; }
;             float dot = (q[0] * k0[0] + q[1] * k0[1]) + (q[2] * k0[2] + q[3] * k0[3]) + (q[4] * k1[0] + q[5] * k1[1]) + (q[6] * k1[2] + q[7] * k1[3]);
;             dot += __shfl_xor(dot, 1); dot += __shfl_xor(dot, 2); dot += __shfl_xor(dot, 4); dot += __shfl_xor(dot, 8);
;             const float s = valid ? dot - sl * (float)(d * j) : -INFINITY;
;             const float mn = fmaxf(m, s), sc = fexp2(m - mn), pe = fexp2(s - mn);
;             l = l * sc + pe;
;             acc[0] = acc[0] * sc + pe * v0[0]; acc[1] = acc[1] * sc + pe * v0[1]; acc[2] = acc[2] * sc + pe * v0[2]; acc[3] = acc[3] * sc + pe * v0[3];
;             acc[4] = acc[4] * sc + pe * v1[0]; acc[5] = acc[5] * sc + pe * v1[1]; acc[6] = acc[6] * sc + pe * v1[2]; acc[7] = acc[7] * sc + pe * v1[3];
;             m = mn;
;         }
;     }
	v_fma_f32 v197, v160, v96, v194
	v_fmac_f32_e32 v197, v161, v97
	v_fmac_f32_e32 v197, v162, v98
	v_fmac_f32_e32 v197, v163, v99
	v_fmac_f32_e32 v197, v164, v100
	v_fmac_f32_e32 v197, v165, v101
	v_fmac_f32_e32 v197, v166, v102
	v_fmac_f32_e32 v197, v167, v103
	s_nop 1
	v_add_f32_dpp v197, v197, v197 row_ror:8 row_mask:0xf bank_mask:0xf
	s_nop 1
	v_add_f32_dpp v197, v197, v197 row_ror:4 row_mask:0xf bank_mask:0xf
	s_nop 1
	v_add_f32_dpp v197, v197, v197 row_ror:2 row_mask:0xf bank_mask:0xf
	s_nop 1
	v_add_f32_dpp v197, v197, v197 row_ror:1 row_mask:0xf bank_mask:0xf
	v_max_f32_e32 v198, v192, v197
	v_sub_f32_e32 v199, v192, v198
	v_sub_f32_e32 v200, v197, v198
	v_exp_f32_e32 v199, v199
	v_exp_f32_e32 v200, v200
	v_mov_b32_e32 v192, v198
	v_fma_f32 v193, v193, v199, v200
	v_mul_f32_e32 v168, v168, v199
	v_mul_f32_e32 v169, v169, v199
	v_mul_f32_e32 v170, v170, v199
	v_mul_f32_e32 v171, v171, v199
	v_mul_f32_e32 v172, v172, v199
	v_mul_f32_e32 v173, v173, v199
	v_mul_f32_e32 v174, v174, v199
	v_mul_f32_e32 v175, v175, v199
	v_fmac_f32_e32 v168, v200, v104
	v_fmac_f32_e32 v169, v200, v105
	v_fmac_f32_e32 v170, v200, v106
	v_fmac_f32_e32 v171, v200, v107
	v_fmac_f32_e32 v172, v200, v108
	v_fmac_f32_e32 v173, v200, v109
	v_fmac_f32_e32 v174, v200, v110
	v_fmac_f32_e32 v175, v200, v111
	v_add_f32_e32 v194, v194, v196
	v_add_u32_e32 v195, s42, v195
	global_load_dwordx4 v[96:99], v195, s[20:21] nt
	global_load_dwordx4 v[100:103], v195, s[20:21] offset:16 nt
	global_load_dwordx4 v[104:107], v195, s[24:25] nt
	global_load_dwordx4 v[108:111], v195, s[24:25] offset:16 nt
	s_waitcnt vmcnt(28)
	v_fma_f32 v197, v160, v112, v194
	v_fmac_f32_e32 v197, v161, v113
	v_fmac_f32_e32 v197, v162, v114
	v_fmac_f32_e32 v197, v163, v115
	v_fmac_f32_e32 v197, v164, v116
	v_fmac_f32_e32 v197, v165, v117
	v_fmac_f32_e32 v197, v166, v118
	v_fmac_f32_e32 v197, v167, v119
	s_nop 1
	v_add_f32_dpp v197, v197, v197 row_ror:8 row_mask:0xf bank_mask:0xf
	s_nop 1
	v_add_f32_dpp v197, v197, v197 row_ror:4 row_mask:0xf bank_mask:0xf
	s_nop 1
	v_add_f32_dpp v197, v197, v197 row_ror:2 row_mask:0xf bank_mask:0xf
	s_nop 1
	v_add_f32_dpp v197, v197, v197 row_ror:1 row_mask:0xf bank_mask:0xf
	v_max_f32_e32 v198, v192, v197
	v_sub_f32_e32 v199, v192, v198
	v_sub_f32_e32 v200, v197, v198
	v_exp_f32_e32 v199, v199
	v_exp_f32_e32 v200, v200
	v_mov_b32_e32 v192, v198
	v_fma_f32 v193, v193, v199, v200
	v_mul_f32_e32 v168, v168, v199
	v_mul_f32_e32 v169, v169, v199
	v_mul_f32_e32 v170, v170, v199
	v_mul_f32_e32 v171, v171, v199
	v_mul_f32_e32 v172, v172, v199
	v_mul_f32_e32 v173, v173, v199
	v_mul_f32_e32 v174, v174, v199
	v_mul_f32_e32 v175, v175, v199
	v_fmac_f32_e32 v168, v200, v120
	v_fmac_f32_e32 v169, v200, v121
	v_fmac_f32_e32 v170, v200, v122
	v_fmac_f32_e32 v171, v200, v123
	v_fmac_f32_e32 v172, v200, v124
	v_fmac_f32_e32 v173, v200, v125
	v_fmac_f32_e32 v174, v200, v126
	v_fmac_f32_e32 v175, v200, v127
	v_add_f32_e32 v194, v194, v196
	v_add_u32_e32 v195, s42, v195
	global_load_dwordx4 v[112:115], v195, s[20:21] nt
	global_load_dwordx4 v[116:119], v195, s[20:21] offset:16 nt
	global_load_dwordx4 v[120:123], v195, s[24:25] nt
	global_load_dwordx4 v[124:127], v195, s[24:25] offset:16 nt
	s_add_u32 s33, s33, 1
	s_cmp_lt_u32 s33, 11
	s_cbranch_scc1 .Las_trip
	s_waitcnt vmcnt(28)
	v_fma_f32 v197, v160, v0, v194
	v_fmac_f32_e32 v197, v161, v1
	v_fmac_f32_e32 v197, v162, v2
	v_fmac_f32_e32 v197, v163, v3
	v_fmac_f32_e32 v197, v164, v4
	v_fmac_f32_e32 v197, v165, v5
	v_fmac_f32_e32 v197, v166, v6
	v_fmac_f32_e32 v197, v167, v7
	s_nop 1
	v_add_f32_dpp v197, v197, v197 row_ror:8 row_mask:0xf bank_mask:0xf
	s_nop 1
	v_add_f32_dpp v197, v197, v197 row_ror:4 row_mask:0xf bank_mask:0xf
	s_nop 1
	v_add_f32_dpp v197, v197, v197 row_ror:2 row_mask:0xf bank_mask:0xf
	s_nop 1
	v_add_f32_dpp v197, v197, v197 row_ror:1 row_mask:0xf bank_mask:0xf
	v_max_f32_e32 v198, v192, v197
	v_sub_f32_e32 v199, v192, v198
	v_sub_f32_e32 v200, v197, v198
	v_exp_f32_e32 v199, v199
	v_exp_f32_e32 v200, v200
	v_mov_b32_e32 v192, v198
	v_fma_f32 v193, v193, v199, v200
	v_mul_f32_e32 v168, v168, v199
	v_mul_f32_e32 v169, v169, v199
	v_mul_f32_e32 v170, v170, v199
	v_mul_f32_e32 v171, v171, v199
	v_mul_f32_e32 v172, v172, v199
	v_mul_f32_e32 v173, v173, v199
	v_mul_f32_e32 v174, v174, v199
	v_mul_f32_e32 v175, v175, v199
	v_fmac_f32_e32 v168, v200, v8
	v_fmac_f32_e32 v169, v200, v9
	v_fmac_f32_e32 v170, v200, v10
	v_fmac_f32_e32 v171, v200, v11
	v_fmac_f32_e32 v172, v200, v12
	v_fmac_f32_e32 v173, v200, v13
	v_fmac_f32_e32 v174, v200, v14
	v_fmac_f32_e32 v175, v200, v15
	v_add_f32_e32 v194, v194, v196
	s_waitcnt vmcnt(24)
	v_fma_f32 v197, v160, v16, v194
	v_fmac_f32_e32 v197, v161, v17
	v_fmac_f32_e32 v197, v162, v18
	v_fmac_f32_e32 v197, v163, v19
	v_fmac_f32_e32 v197, v164, v20
	v_fmac_f32_e32 v197, v165, v21
	v_fmac_f32_e32 v197, v166, v22
	v_fmac_f32_e32 v197, v167, v23
	s_nop 1
	v_add_f32_dpp v197, v197, v197 row_ror:8 row_mask:0xf bank_mask:0xf
	s_nop 1
	v_add_f32_dpp v197, v197, v197 row_ror:4 row_mask:0xf bank_mask:0xf
	s_nop 1
	v_add_f32_dpp v197, v197, v197 row_ror:2 row_mask:0xf bank_mask:0xf
	s_nop 1
	v_add_f32_dpp v197, v197, v197 row_ror:1 row_mask:0xf bank_mask:0xf
	v_max_f32_e32 v198, v192, v197
	v_sub_f32_e32 v199, v192, v198
	v_sub_f32_e32 v200, v197, v198
	v_exp_f32_e32 v199, v199
	v_exp_f32_e32 v200, v200
	v_mov_b32_e32 v192, v198
	v_fma_f32 v193, v193, v199, v200
	v_mul_f32_e32 v168, v168, v199
	v_mul_f32_e32 v169, v169, v199
	v_mul_f32_e32 v170, v170, v199
	v_mul_f32_e32 v171, v171, v199
	v_mul_f32_e32 v172, v172, v199
	v_mul_f32_e32 v173, v173, v199
	v_mul_f32_e32 v174, v174, v199
	v_mul_f32_e32 v175, v175, v199
	v_fmac_f32_e32 v168, v200, v24
	v_fmac_f32_e32 v169, v200, v25
	v_fmac_f32_e32 v170, v200, v26
	v_fmac_f32_e32 v171, v200, v27
	v_fmac_f32_e32 v172, v200, v28
	v_fmac_f32_e32 v173, v200, v29
	v_fmac_f32_e32 v174, v200, v30
	v_fmac_f32_e32 v175, v200, v31
	v_add_f32_e32 v194, v194, v196
	s_waitcnt vmcnt(20)
; __device__ __forceinline__ float fexp2(float x) { return __builtin_amdgcn_exp2f(x); }
; __device__ __forceinline__ void attn_sample_item(const P& p, int wi, int lane) {
;     ...
;         for (int jj = 0; jj < 33; ++jj) {
;             const int j = 4 * jj + kg; const bool valid = j <= 128; const int jc = valid ? j : 128;
;             const int idx = 2048 + i - d * jc;
;             f32x4 k0, k1, v0, v1;
;             if (idx < 2048) { const size_t off = (((size_t)bs * 2048 + idx) * 8 + h) * 128 + 8 * li;
;                 k0 = __builtin_nontemporal_load((const f32x4*)(p.cache_k + off)); k1 = __builtin_nontemporal_load((const f32x4*)(p.cache_k + off + 4)); v0 = __builtin_nontemporal_load((const f32x4*)(p.cache_v + off)); v1 = __builtin_nontemporal_load((const f32x4*)(p.cache_v + off + 4)); }
;             else { const int nr = bs * 4 + (idx - 2048); const float rsn = rstd1[TP + nr]; const int c0 = 4096 + h * 128 + 8 * li;
;                 k0 = acc1_4(ACC1, nr, c0) * rsn; k1 = acc1_4(ACC1, nr, c0 + 4) * rsn; v0 = acc1_4(ACC1, nr, c0 + 1024) * rsn; v1 = acc1_4(ACC1, nr, c0 + 1028) * rsn; }
;             float dot = (q[0] * k0[0] + q[1] * k0[1]) + (q[2] * k0[2] + q[3] * k0[3]) + (q[4] * k1[0] + q[5] * k1[1]) + (q[6] * k1[2] + q[7] * k1[3]);
;             dot += __shfl_xor(dot, 1); dot += __shfl_xor(dot, 2); dot += __shfl_xor(dot, 4); dot += __shfl_xor(dot, 8);
;             const float s = valid ? dot - sl * (float)(d * j) : -INFINITY;
;             const float mn = fmaxf(m, s), sc = fexp2(m - mn), pe = fexp2(s - mn);
;             l = l * sc + pe;
;             acc[0] = acc[0] * sc + pe * v0[0]; acc[1] = acc[1] * sc + pe * v0[1]; acc[2] = acc[2] * sc + pe * v0[2]; acc[3] = acc[3] * sc + pe * v0[3];
;             acc[4] = acc[4] * sc + pe * v1[0]; acc[5] = acc[5] * sc + pe * v1[1]; acc[6] = acc[6] * sc + pe * v1[2]; acc[7] = acc[7] * sc + pe * v1[3];
;             m = mn;
	v_fma_f32 v197, v160, v32, v194
	v_fmac_f32_e32 v197, v161, v33
	v_fmac_f32_e32 v197, v162, v34
	v_fmac_f32_e32 v197, v163, v35
	v_fmac_f32_e32 v197, v164, v36
	v_fmac_f32_e32 v197, v165, v37
	v_fmac_f32_e32 v197, v166, v38
	v_fmac_f32_e32 v197, v167, v39
	s_nop 1
	v_add_f32_dpp v197, v197, v197 row_ror:8 row_mask:0xf bank_mask:0xf
	s_nop 1
	v_add_f32_dpp v197, v197, v197 row_ror:4 row_mask:0xf bank_mask:0xf
	s_nop 1
	v_add_f32_dpp v197, v197, v197 row_ror:2 row_mask:0xf bank_mask:0xf
	s_nop 1
	v_add_f32_dpp v197, v197, v197 row_ror:1 row_mask:0xf bank_mask:0xf
	v_max_f32_e32 v198, v192, v197
	v_sub_f32_e32 v199, v192, v198
	v_sub_f32_e32 v200, v197, v198
	v_exp_f32_e32 v199, v199
	v_exp_f32_e32 v200, v200
	v_mov_b32_e32 v192, v198
	v_fma_f32 v193, v193, v199, v200
	v_mul_f32_e32 v168, v168, v199
	v_mul_f32_e32 v169, v169, v199
	v_mul_f32_e32 v170, v170, v199
	v_mul_f32_e32 v171, v171, v199
	v_mul_f32_e32 v172, v172, v199
	v_mul_f32_e32 v173, v173, v199
	v_mul_f32_e32 v174, v174, v199
	v_mul_f32_e32 v175, v175, v199
	v_fmac_f32_e32 v168, v200, v40
	v_fmac_f32_e32 v169, v200, v41
	v_fmac_f32_e32 v170, v200, v42
	v_fmac_f32_e32 v171, v200, v43
	v_fmac_f32_e32 v172, v200, v44
	v_fmac_f32_e32 v173, v200, v45
	v_fmac_f32_e32 v174, v200, v46
	v_fmac_f32_e32 v175, v200, v47
	v_add_f32_e32 v194, v194, v196
	s_waitcnt vmcnt(16)
	v_fma_f32 v197, v160, v48, v194
	v_fmac_f32_e32 v197, v161, v49
	v_fmac_f32_e32 v197, v162, v50
	v_fmac_f32_e32 v197, v163, v51
	v_fmac_f32_e32 v197, v164, v52
	v_fmac_f32_e32 v197, v165, v53
	v_fmac_f32_e32 v197, v166, v54
	v_fmac_f32_e32 v197, v167, v55
	s_nop 1
	v_add_f32_dpp v197, v197, v197 row_ror:8 row_mask:0xf bank_mask:0xf
	s_nop 1
	v_add_f32_dpp v197, v197, v197 row_ror:4 row_mask:0xf bank_mask:0xf
	s_nop 1
	v_add_f32_dpp v197, v197, v197 row_ror:2 row_mask:0xf bank_mask:0xf
	s_nop 1
	v_add_f32_dpp v197, v197, v197 row_ror:1 row_mask:0xf bank_mask:0xf
	v_max_f32_e32 v198, v192, v197
	v_sub_f32_e32 v199, v192, v198
	v_sub_f32_e32 v200, v197, v198
	v_exp_f32_e32 v199, v199
	v_exp_f32_e32 v200, v200
	v_mov_b32_e32 v192, v198
	v_fma_f32 v193, v193, v199, v200
	v_mul_f32_e32 v168, v168, v199
	v_mul_f32_e32 v169, v169, v199
	v_mul_f32_e32 v170, v170, v199
	v_mul_f32_e32 v171, v171, v199
	v_mul_f32_e32 v172, v172, v199
	v_mul_f32_e32 v173, v173, v199
	v_mul_f32_e32 v174, v174, v199
	v_mul_f32_e32 v175, v175, v199
	v_fmac_f32_e32 v168, v200, v56
	v_fmac_f32_e32 v169, v200, v57
	v_fmac_f32_e32 v170, v200, v58
	v_fmac_f32_e32 v171, v200, v59
	v_fmac_f32_e32 v172, v200, v60
	v_fmac_f32_e32 v173, v200, v61
	v_fmac_f32_e32 v174, v200, v62
	v_fmac_f32_e32 v175, v200, v63
	v_add_f32_e32 v194, v194, v196
	s_waitcnt vmcnt(12)
	v_fma_f32 v197, v160, v64, v194
	v_fmac_f32_e32 v197, v161, v65
	v_fmac_f32_e32 v197, v162, v66
	v_fmac_f32_e32 v197, v163, v67
	v_fmac_f32_e32 v197, v164, v68
	v_fmac_f32_e32 v197, v165, v69
	v_fmac_f32_e32 v197, v166, v70
	v_fmac_f32_e32 v197, v167, v71
	s_nop 1
	v_add_f32_dpp v197, v197, v197 row_ror:8 row_mask:0xf bank_mask:0xf
	s_nop 1
	v_add_f32_dpp v197, v197, v197 row_ror:4 row_mask:0xf bank_mask:0xf
	s_nop 1
	v_add_f32_dpp v197, v197, v197 row_ror:2 row_mask:0xf bank_mask:0xf
	s_nop 1
	v_add_f32_dpp v197, v197, v197 row_ror:1 row_mask:0xf bank_mask:0xf
	v_max_f32_e32 v198, v192, v197
	v_sub_f32_e32 v199, v192, v198
	v_sub_f32_e32 v200, v197, v198
	v_exp_f32_e32 v199, v199
	v_exp_f32_e32 v200, v200
	v_mov_b32_e32 v192, v198
	v_fma_f32 v193, v193, v199, v200
	v_mul_f32_e32 v168, v168, v199
	v_mul_f32_e32 v169, v169, v199
	v_mul_f32_e32 v170, v170, v199
	v_mul_f32_e32 v171, v171, v199
	v_mul_f32_e32 v172, v172, v199
	v_mul_f32_e32 v173, v173, v199
	v_mul_f32_e32 v174, v174, v199
	v_mul_f32_e32 v175, v175, v199
	v_fmac_f32_e32 v168, v200, v72
	v_fmac_f32_e32 v169, v200, v73
	v_fmac_f32_e32 v170, v200, v74
	v_fmac_f32_e32 v171, v200, v75
	v_fmac_f32_e32 v172, v200, v76
	v_fmac_f32_e32 v173, v200, v77
	v_fmac_f32_e32 v174, v200, v78
	v_fmac_f32_e32 v175, v200, v79
	v_add_f32_e32 v194, v194, v196
	s_waitcnt vmcnt(8)
	v_fma_f32 v197, v160, v80, v194
	v_fmac_f32_e32 v197, v161, v81
	v_fmac_f32_e32 v197, v162, v82
	v_fmac_f32_e32 v197, v163, v83
	v_fmac_f32_e32 v197, v164, v84
	v_fmac_f32_e32 v197, v165, v85
	v_fmac_f32_e32 v197, v166, v86
	v_fmac_f32_e32 v197, v167, v87
	s_nop 1
	v_add_f32_dpp v197, v197, v197 row_ror:8 row_mask:0xf bank_mask:0xf
	s_nop 1
	v_add_f32_dpp v197, v197, v197 row_ror:4 row_mask:0xf bank_mask:0xf
	s_nop 1
	v_add_f32_dpp v197, v197, v197 row_ror:2 row_mask:0xf bank_mask:0xf
	s_nop 1
	v_add_f32_dpp v197, v197, v197 row_ror:1 row_mask:0xf bank_mask:0xf
	v_max_f32_e32 v198, v192, v197
	v_sub_f32_e32 v199, v192, v198
	v_sub_f32_e32 v200, v197, v198
	v_exp_f32_e32 v199, v199
	v_exp_f32_e32 v200, v200
	v_mov_b32_e32 v192, v198
	v_fma_f32 v193, v193, v199, v200
	v_mul_f32_e32 v168, v168, v199
	v_mul_f32_e32 v169, v169, v199
	v_mul_f32_e32 v170, v170, v199
	v_mul_f32_e32 v171, v171, v199
	v_mul_f32_e32 v172, v172, v199
	v_mul_f32_e32 v173, v173, v199
	v_mul_f32_e32 v174, v174, v199
	v_mul_f32_e32 v175, v175, v199
	v_fmac_f32_e32 v168, v200, v88
	v_fmac_f32_e32 v169, v200, v89
	v_fmac_f32_e32 v170, v200, v90
	v_fmac_f32_e32 v171, v200, v91
	v_fmac_f32_e32 v172, v200, v92
	v_fmac_f32_e32 v173, v200, v93
	v_fmac_f32_e32 v174, v200, v94
	v_fmac_f32_e32 v175, v200, v95
	v_add_f32_e32 v194, v194, v196
	s_waitcnt vmcnt(4)
; __device__ __forceinline__ float fexp2(float x) { return __builtin_amdgcn_exp2f(x); }
; __device__ __forceinline__ void attn_sample_item(const P& p, int wi, int lane) {
;     ...
;     float mt = fmaxf(m, __shfl_xor(m, 16)); mt = fmaxf(mt, __shfl_xor(mt, 32));
;     const float f = fexp2(m - mt);
;     l *= f; l += __shfl_xor(l, 16); l += __shfl_xor(l, 32);
;     const float inv = 1.f / l;
;     float* o = (float*)(ws + O_ATTS) + (size_t)srow * 1024 + h * 128 + 8 * li;
; #pragma unroll
;     for (int e = 0; e < 8; ++e) { float a = acc[e] * f; a += __shfl_xor(a, 16); a += __shfl_xor(a, 32); acc[e] = a * inv; }
;     if (kg == 0) { *(f32x4*)o = (f32x4){acc[0], acc[1], acc[2], acc[3]}; *(f32x4*)(o + 4) = (f32x4){acc[4], acc[5], acc[6], acc[7]}; }
; __global__ void __launch_bounds__(NTHR) fwd_megakernel(P p) {
;     ...
;           if (w < 4) { for (int wi = w * G + blockIdx.x; wi < 1024; wi += G * 4) attn_sample_item(p, wi, t0 & 63); }
	v_fma_f32 v197, v160, v96, v194
	v_fmac_f32_e32 v197, v161, v97
	v_fmac_f32_e32 v197, v162, v98
	v_fmac_f32_e32 v197, v163, v99
	v_fmac_f32_e32 v197, v164, v100
	v_fmac_f32_e32 v197, v165, v101
	v_fmac_f32_e32 v197, v166, v102
	v_fmac_f32_e32 v197, v167, v103
	s_nop 1
	v_add_f32_dpp v197, v197, v197 row_ror:8 row_mask:0xf bank_mask:0xf
	s_nop 1
	v_add_f32_dpp v197, v197, v197 row_ror:4 row_mask:0xf bank_mask:0xf
	s_nop 1
	v_add_f32_dpp v197, v197, v197 row_ror:2 row_mask:0xf bank_mask:0xf
	s_nop 1
	v_add_f32_dpp v197, v197, v197 row_ror:1 row_mask:0xf bank_mask:0xf
	v_max_f32_e32 v198, v192, v197
	v_sub_f32_e32 v199, v192, v198
	v_sub_f32_e32 v200, v197, v198
	v_exp_f32_e32 v199, v199
	v_exp_f32_e32 v200, v200
	v_mov_b32_e32 v192, v198
	v_fma_f32 v193, v193, v199, v200
	v_mul_f32_e32 v168, v168, v199
	v_mul_f32_e32 v169, v169, v199
	v_mul_f32_e32 v170, v170, v199
	v_mul_f32_e32 v171, v171, v199
	v_mul_f32_e32 v172, v172, v199
	v_mul_f32_e32 v173, v173, v199
	v_mul_f32_e32 v174, v174, v199
	v_mul_f32_e32 v175, v175, v199
	v_fmac_f32_e32 v168, v200, v104
	v_fmac_f32_e32 v169, v200, v105
	v_fmac_f32_e32 v170, v200, v106
	v_fmac_f32_e32 v171, v200, v107
	v_fmac_f32_e32 v172, v200, v108
	v_fmac_f32_e32 v173, v200, v109
	v_fmac_f32_e32 v174, v200, v110
	v_fmac_f32_e32 v175, v200, v111
	v_add_f32_e32 v194, v194, v196
	s_waitcnt vmcnt(0)
	v_fma_f32 v197, v160, v112, v194
	v_fmac_f32_e32 v197, v161, v113
	v_fmac_f32_e32 v197, v162, v114
	v_fmac_f32_e32 v197, v163, v115
	v_fmac_f32_e32 v197, v164, v116
	v_fmac_f32_e32 v197, v165, v117
	v_fmac_f32_e32 v197, v166, v118
	v_fmac_f32_e32 v197, v167, v119
	s_nop 1
	v_add_f32_dpp v197, v197, v197 row_ror:8 row_mask:0xf bank_mask:0xf
	s_nop 1
	v_add_f32_dpp v197, v197, v197 row_ror:4 row_mask:0xf bank_mask:0xf
	s_nop 1
	v_add_f32_dpp v197, v197, v197 row_ror:2 row_mask:0xf bank_mask:0xf
	s_nop 1
	v_add_f32_dpp v197, v197, v197 row_ror:1 row_mask:0xf bank_mask:0xf
	v_max_f32_e32 v198, v192, v197
	v_sub_f32_e32 v199, v192, v198
	v_sub_f32_e32 v200, v197, v198
	v_exp_f32_e32 v199, v199
	v_exp_f32_e32 v200, v200
	v_mov_b32_e32 v192, v198
	v_fma_f32 v193, v193, v199, v200
	v_mul_f32_e32 v168, v168, v199
	v_mul_f32_e32 v169, v169, v199
	v_mul_f32_e32 v170, v170, v199
	v_mul_f32_e32 v171, v171, v199
	v_mul_f32_e32 v172, v172, v199
	v_mul_f32_e32 v173, v173, v199
	v_mul_f32_e32 v174, v174, v199
	v_mul_f32_e32 v175, v175, v199
	v_fmac_f32_e32 v168, v200, v120
	v_fmac_f32_e32 v169, v200, v121
	v_fmac_f32_e32 v170, v200, v122
	v_fmac_f32_e32 v171, v200, v123
	v_fmac_f32_e32 v172, v200, v124
	v_fmac_f32_e32 v173, v200, v125
	v_fmac_f32_e32 v174, v200, v126
	v_fmac_f32_e32 v175, v200, v127
	v_and_b32_e32 v182, 63, v230
	v_xor_b32_e32 v183, 16, v182
	v_lshlrev_b32_e32 v183, 2, v183
	v_xor_b32_e32 v182, 32, v182
	v_lshlrev_b32_e32 v182, 2, v182
	ds_bpermute_b32 v197, v183, v192
	s_waitcnt lgkmcnt(0)
	v_max_f32_e32 v198, v192, v197
	ds_bpermute_b32 v197, v182, v198
	s_waitcnt lgkmcnt(0)
	v_max_f32_e32 v198, v198, v197
	v_sub_f32_e32 v199, v192, v198
	v_exp_f32_e32 v199, v199
	s_nop 0
	v_mul_f32_e32 v193, v193, v199
	v_mul_f32_e32 v168, v168, v199
	v_mul_f32_e32 v169, v169, v199
	v_mul_f32_e32 v170, v170, v199
	v_mul_f32_e32 v171, v171, v199
	v_mul_f32_e32 v172, v172, v199
	v_mul_f32_e32 v173, v173, v199
	v_mul_f32_e32 v174, v174, v199
	v_mul_f32_e32 v175, v175, v199
	ds_bpermute_b32 v0, v183, v193
	ds_bpermute_b32 v1, v183, v168
	ds_bpermute_b32 v2, v183, v169
	ds_bpermute_b32 v3, v183, v170
	ds_bpermute_b32 v4, v183, v171
	ds_bpermute_b32 v5, v183, v172
	ds_bpermute_b32 v6, v183, v173
	ds_bpermute_b32 v7, v183, v174
	ds_bpermute_b32 v8, v183, v175
	s_waitcnt lgkmcnt(0)
	v_add_f32_e32 v193, v193, v0
	v_add_f32_e32 v168, v168, v1
	v_add_f32_e32 v169, v169, v2
	v_add_f32_e32 v170, v170, v3
	v_add_f32_e32 v171, v171, v4
	v_add_f32_e32 v172, v172, v5
	v_add_f32_e32 v173, v173, v6
	v_add_f32_e32 v174, v174, v7
	v_add_f32_e32 v175, v175, v8
	ds_bpermute_b32 v0, v182, v193
	ds_bpermute_b32 v1, v182, v168
	ds_bpermute_b32 v2, v182, v169
	ds_bpermute_b32 v3, v182, v170
	ds_bpermute_b32 v4, v182, v171
	ds_bpermute_b32 v5, v182, v172
	ds_bpermute_b32 v6, v182, v173
	ds_bpermute_b32 v7, v182, v174
	ds_bpermute_b32 v8, v182, v175
	s_waitcnt lgkmcnt(0)
	v_add_f32_e32 v193, v193, v0
	v_add_f32_e32 v168, v168, v1
	v_add_f32_e32 v169, v169, v2
	v_add_f32_e32 v170, v170, v3
	v_add_f32_e32 v171, v171, v4
	v_add_f32_e32 v172, v172, v5
	v_add_f32_e32 v173, v173, v6
	v_add_f32_e32 v174, v174, v7
	v_add_f32_e32 v175, v175, v8
	v_rcp_f32_e32 v197, v193
	s_nop 0
	v_fma_f32 v198, -v193, v197, 1.0
	v_fma_f32 v197, v198, v197, v197
	v_mul_f32_e32 v168, v168, v197
	v_mul_f32_e32 v169, v169, v197
	v_mul_f32_e32 v170, v170, v197
	v_mul_f32_e32 v171, v171, v197
	v_mul_f32_e32 v172, v172, v197
	v_mul_f32_e32 v173, v173, v197
	v_mul_f32_e32 v174, v174, v197
	v_mul_f32_e32 v175, v175, v197
	v_and_b32_e32 v182, 15, v230
	v_lshlrev_b32_e32 v182, 5, v182
	s_lshl_b32 s43, s17, 12
	s_add_u32 s43, s43, s23
	v_add_u32_e32 v182, s43, v182
	s_mov_b64 exec, 0xffff
	global_store_dwordx4 v182, v[168:171], s[30:31]
	global_store_dwordx4 v182, v[172:175], s[30:31] offset:16
	s_mov_b64 exec, -1
	s_add_i32 s3, s3, s77
	s_cmpk_gt_i32 s3, 0x3ff
	s_cbranch_scc0 .Las_item
